# P4 epilogue: GroupNorm weight/bias vectors of all four channel groups loaded together; no vmcnt(0) drains between groups
# speedup vs baseline: 1.0080x; 1.0020x over previous
.LBB0_532:
	v_add_u32_e32 v72, 1, v118
	v_cvt_f32_i32_e32 v72, v72
	v_ashrrev_i32_e32 v119, 31, v118
	s_lshl_b32 s0, s19, 6
	s_waitcnt vmcnt(4)
	v_lshlrev_b32_e32 v144, 16, v30
	v_mul_f32_e32 v72, v92, v72
	v_exp_f32_e32 v72, v72
	v_and_b32_e32 v145, 0xffff0000, v30
	v_lshlrev_b32_e32 v150, 16, v31
	v_and_b32_e32 v151, 0xffff0000, v31
	v_pk_fma_f32 v[70:71], v[72:73], v[70:71], v[90:91] op_sel_hi:[0,1,1]
	v_pk_fma_f32 v[68:69], v[72:73], v[68:69], v[88:89] op_sel_hi:[0,1,1]
	v_pk_mov_b32 v[74:75], v[68:69], v[70:71] op_sel:[1,0]
	v_mov_b32_e32 v76, v68
	v_mov_b32_e32 v77, v71
	v_pk_add_f32 v[74:75], v[74:75], v[76:77]
	v_pk_fma_f32 v[66:67], v[72:73], v[66:67], v[86:87] op_sel_hi:[0,1,1]
	v_pk_fma_f32 v[64:65], v[72:73], v[64:65], v[84:85] op_sel_hi:[0,1,1]
	v_add_f32_e32 v73, v74, v75
	v_pk_mov_b32 v[78:79], v[64:65], v[66:67] op_sel:[1,0]
	v_add_f32_e32 v73, 0, v73
	v_mov_b32_e32 v74, v64
	v_mov_b32_e32 v75, v67
	v_pk_add_f32 v[74:75], v[78:79], v[74:75]
	v_pk_fma_f32 v[62:63], v[72:73], v[62:63], v[82:83] op_sel_hi:[0,1,1]
	v_pk_fma_f32 v[54:55], v[72:73], v[54:55], v[58:59] op_sel_hi:[0,1,1]
	v_lshl_add_u64 v[82:83], s[34:35], 0, v[118:119]
	v_mov_b64_e32 v[58:59], s[68:69]
	v_pk_add_f32 v[74:75], v[74:75], v[74:75] op_sel_hi:[0,1]
	v_mad_u64_u32 v[58:59], s[4:5], v82, s17, v[58:59]
	v_mov_b32_e32 v74, v59
	v_pk_fma_f32 v[60:61], v[72:73], v[60:61], v[80:81] op_sel_hi:[0,1,1]
	v_or_b32_e32 v86, s0, v127
	v_mad_u64_u32 v[80:81], s[4:5], v83, s17, v[74:75]
	v_mov_b32_e32 v59, v80
	v_lshlrev_b32_e32 v92, 1, v86
	v_lshl_add_u64 v[58:59], v[58:59], 0, v[92:93]
	global_load_dwordx2 v[84:85], v[58:59], off offset:3072
	v_pk_fma_f32 v[52:53], v[72:73], v[52:53], v[56:57] op_sel_hi:[0,1,1]
	v_add_f32_e32 v77, v60, v61
	v_add_f32_e32 v79, v62, v63
	v_mov_b32_e32 v76, v52
	v_mov_b32_e32 v78, v53
	v_mov_b32_e32 v74, v54
	v_mov_b32_e32 v72, v55
	v_pk_add_f32 v[56:57], v[76:77], v[78:79]
	v_pk_add_f32 v[72:73], v[74:75], v[72:73]
	v_lshlrev_b64 v[82:83], 11, v[82:83]
	v_pk_add_f32 v[56:57], v[56:57], v[72:73]
	v_lshl_add_u64 v[82:83], s[90:91], 0, v[82:83]
	v_add_f32_e32 v56, v56, v57
	ds_bpermute_b32 v57, v128, v56
	v_lshlrev_b32_e32 v142, 16, v34
	v_and_b32_e32 v143, 0xffff0000, v34
	v_lshlrev_b32_e32 v148, 16, v35
	v_and_b32_e32 v149, 0xffff0000, v35
	s_waitcnt lgkmcnt(0)
	v_add_f32_e32 v56, v56, v57
	ds_bpermute_b32 v57, v129, v56
	v_lshlrev_b32_e32 v118, 16, v38
	v_and_b32_e32 v119, 0xffff0000, v38
	v_lshlrev_b32_e32 v38, 16, v39
	v_and_b32_e32 v39, 0xffff0000, v39
	s_waitcnt lgkmcnt(0)
	v_add_f32_e32 v107, v56, v57
	v_lshlrev_b32_e32 v57, 2, v86
	global_load_dwordx4 v[74:77], v57, s[36:37]
	global_load_dwordx4 v[78:81], v57, s[38:39]
	global_load_dwordx4 v[196:199], v57, s[36:37] offset:64
	global_load_dwordx4 v[200:203], v57, s[38:39] offset:64
	global_load_dwordx4 v[204:207], v57, s[36:37] offset:128
	global_load_dwordx4 v[208:211], v57, s[38:39] offset:128
	global_load_dwordx4 v[212:215], v57, s[36:37] offset:192
	global_load_dwordx4 v[216:219], v57, s[38:39] offset:192
	v_fmamk_f32 v69, v107, 0xbc800000, v69
	v_fmac_f32_e32 v68, 0xbc800000, v107
	v_fmamk_f32 v71, v107, 0xbc800000, v71
	v_fmac_f32_e32 v70, 0xbc800000, v107
	v_pk_mul_f32 v[72:73], v[70:71], v[70:71]
	v_pk_mul_f32 v[86:87], v[68:69], v[68:69]
	v_fmamk_f32 v65, v107, 0xbc800000, v65
	v_pk_mov_b32 v[88:89], v[86:87], v[72:73] op_sel:[1,0]
	v_mov_b32_e32 v87, v73
	v_fmac_f32_e32 v64, 0xbc800000, v107
	v_fmamk_f32 v67, v107, 0xbc800000, v67
	v_fmac_f32_e32 v66, 0xbc800000, v107
	v_pk_add_f32 v[72:73], v[88:89], v[86:87]
	v_pk_mul_f32 v[86:87], v[66:67], v[66:67]
	v_pk_mul_f32 v[88:89], v[64:65], v[64:65]
	v_fmac_f32_e32 v60, 0xbc800000, v107
	v_pk_mov_b32 v[90:91], v[88:89], v[86:87] op_sel:[1,0]
	v_mov_b32_e32 v89, v87
	v_fmac_f32_e32 v62, 0xbc800000, v107
	v_fmamk_f32 v61, v107, 0xbc800000, v61
	v_mul_f32_e32 v56, v60, v60
	v_pk_add_f32 v[86:87], v[90:91], v[88:89]
	v_fmamk_f32 v63, v107, 0xbc800000, v63
	v_pk_fma_f32 v[88:89], v[60:61], v[60:61], v[56:57] op_sel_hi:[1,1,0]
	v_mul_f32_e32 v56, v62, v62
	v_pk_add_f32 v[72:73], v[72:73], v[72:73] op_sel_hi:[0,1]
	v_pk_add_f32 v[86:87], v[86:87], v[86:87] op_sel_hi:[0,1]
	v_pk_fma_f32 v[90:91], v[62:63], v[62:63], v[56:57] op_sel_hi:[1,1,0]
	v_fmamk_f32 v55, v107, 0xbc800000, v55
	v_fmac_f32_e32 v54, 0xbc800000, v107
	v_fmamk_f32 v53, v107, 0xbc800000, v53
	v_fmac_f32_e32 v52, 0xbc800000, v107
	v_mul_f32_e32 v88, v52, v52
	v_mul_f32_e32 v90, v53, v53
	v_mul_f32_e32 v72, v54, v54
	v_mul_f32_e32 v86, v55, v55
	v_pk_add_f32 v[88:89], v[88:89], v[90:91]
	v_pk_add_f32 v[72:73], v[72:73], v[86:87]
	s_waitcnt vmcnt(12)
	v_lshlrev_b32_e32 v138, 16, v42
	v_pk_add_f32 v[72:73], v[88:89], v[72:73]
	v_and_b32_e32 v139, 0xffff0000, v42
	v_add_f32_e32 v56, v72, v73
	ds_bpermute_b32 v72, v128, v56
	v_lshlrev_b32_e32 v42, 16, v43
	v_and_b32_e32 v43, 0xffff0000, v43
	s_waitcnt vmcnt(9)
	v_lshlrev_b32_e32 v140, 16, v50
	v_and_b32_e32 v141, 0xffff0000, v50
	s_waitcnt lgkmcnt(0)
	v_add_f32_e32 v56, v56, v72
	ds_bpermute_b32 v72, v129, v56
	v_lshlrev_b32_e32 v146, 16, v46
	v_and_b32_e32 v147, 0xffff0000, v46
	v_lshlrev_b32_e32 v46, 16, v47
	s_waitcnt vmcnt(8)
	v_lshlrev_b32_e32 v88, 16, v84
	v_and_b32_e32 v89, 0xffff0000, v84
	v_mul_f32_e32 v84, 0xbfb8aa3b, v88
	v_exp_f32_e32 v84, v84
	v_mul_f32_e32 v90, 0xbfb8aa3b, v89
	v_exp_f32_e32 v91, v90
	s_waitcnt lgkmcnt(0)
	v_add_f32_e32 v56, v56, v72
	v_add_f32_e32 v84, 1.0, v84
	v_rcp_f32_e32 v90, v84
	v_add_f32_e32 v84, 1.0, v91
	v_rcp_f32_e32 v91, v84
	v_lshlrev_b32_e32 v84, 16, v85
	v_and_b32_e32 v85, 0xffff0000, v85
	v_fmamk_f32 v56, v56, 0x3c800000, v136
	v_pk_mul_f32 v[88:89], v[90:91], v[88:89]
	v_mul_f32_e32 v90, 0xbfb8aa3b, v84
	v_mul_f32_e32 v91, 0xbfb8aa3b, v85
	v_exp_f32_e32 v90, v90
	v_exp_f32_e32 v91, v91
	v_rsq_f32_e32 v56, v56
	global_load_dwordx2 v[86:87], v[58:59], off offset:3104
	global_load_dwordx2 v[72:73], v[58:59], off offset:3136
	s_nop 0
	global_load_dwordx2 v[58:59], v[58:59], off offset:3168
	v_add_f32_e32 v90, 1.0, v90
	v_add_f32_e32 v91, 1.0, v91
	v_rcp_f32_e32 v90, v90
	v_rcp_f32_e32 v91, v91
	v_pk_mul_f32 v[68:69], v[68:69], v[56:57] op_sel_hi:[1,0]
	v_pk_mul_f32 v[70:71], v[70:71], v[56:57] op_sel_hi:[1,0]
	s_waitcnt vmcnt(9)
	v_pk_fma_f32 v[68:69], v[74:75], v[68:69], v[78:79]
	v_pk_fma_f32 v[70:71], v[76:77], v[70:71], v[80:81]
	v_pk_mul_f32 v[68:69], v[88:89], v[68:69]
	v_pk_mul_f32 v[64:65], v[64:65], v[56:57] op_sel_hi:[1,0]
	v_cvt_pk_bf16_f32 v74, v68, v69
	v_pk_mul_f32 v[68:69], v[90:91], v[84:85]
	v_pk_mul_f32 v[66:67], v[66:67], v[56:57] op_sel_hi:[1,0]
	v_pk_mul_f32 v[68:69], v[68:69], v[70:71]
	v_lshlrev_b32_e32 v90, 16, v29
	v_cvt_pk_bf16_f32 v75, v68, v69
	v_lshl_add_u64 v[68:69], v[82:83], 0, v[92:93]
	global_store_dwordx2 v[68:69], v[74:75], off
	s_waitcnt vmcnt(4)
	v_mov_b32_e32 v78, v200
	v_mov_b32_e32 v79, v201
	v_mov_b32_e32 v80, v202
	v_mov_b32_e32 v81, v203
	v_mov_b32_e32 v76, v198
	v_mov_b32_e32 v77, v199
	v_mov_b32_e32 v74, v196
	v_mov_b32_e32 v75, v197
	v_and_b32_e32 v91, 0xffff0000, v29
	v_lshlrev_b32_e32 v88, 16, v33
	v_and_b32_e32 v89, 0xffff0000, v33
	v_pk_mul_f32 v[60:61], v[60:61], v[56:57] op_sel_hi:[1,0]
	v_pk_mul_f32 v[62:63], v[62:63], v[56:57] op_sel_hi:[1,0]
	v_max_f32_e32 v92, v110, v110
	v_and_b32_e32 v47, 0xffff0000, v47
	v_lshlrev_b32_e32 v50, 16, v51
	v_and_b32_e32 v51, 0xffff0000, v51
	v_lshlrev_b64 v[114:115], 11, v[114:115]
	s_lshl_b32 s2, s0, 1
	v_mov_b32_e32 v109, v93
	s_andn2_b64 vcc, exec, s[30:31]
	s_mov_b32 s0, s18
	s_waitcnt vmcnt(3)
	v_lshlrev_b32_e32 v70, 16, v86
	v_and_b32_e32 v71, 0xffff0000, v86
	v_lshlrev_b32_e32 v82, 16, v87
	v_and_b32_e32 v83, 0xffff0000, v87
	v_mul_f32_e32 v84, 0xbfb8aa3b, v70
	v_mul_f32_e32 v85, 0xbfb8aa3b, v71
	v_mul_f32_e32 v86, 0xbfb8aa3b, v82
	v_mul_f32_e32 v87, 0xbfb8aa3b, v83
	v_exp_f32_e32 v84, v84
	v_exp_f32_e32 v85, v85
	v_exp_f32_e32 v86, v86
	v_exp_f32_e32 v87, v87
	v_add_f32_e32 v84, 1.0, v84
	v_add_f32_e32 v85, 1.0, v85
	v_add_f32_e32 v86, 1.0, v86
	v_add_f32_e32 v87, 1.0, v87
	v_rcp_f32_e32 v84, v84
	v_rcp_f32_e32 v85, v85
	v_rcp_f32_e32 v86, v86
	v_rcp_f32_e32 v87, v87
	s_waitcnt vmcnt(2)
	v_and_b32_e32 v29, 0xffff0000, v72
	v_pk_mul_f32 v[70:71], v[84:85], v[70:71]
	s_waitcnt vmcnt(1)
	v_pk_fma_f32 v[64:65], v[74:75], v[64:65], v[78:79]
	v_pk_mul_f32 v[82:83], v[86:87], v[82:83]
	v_pk_fma_f32 v[66:67], v[76:77], v[66:67], v[80:81]
	v_pk_mul_f32 v[64:65], v[70:71], v[64:65]
	v_pk_mul_f32 v[66:67], v[82:83], v[66:67]
	v_cvt_pk_bf16_f32 v64, v64, v65
	v_cvt_pk_bf16_f32 v65, v66, v67
	global_store_dwordx2 v[68:69], v[64:65], off offset:32
	v_mov_b32_e32 v74, v208
	v_mov_b32_e32 v75, v209
	v_mov_b32_e32 v76, v210
	v_mov_b32_e32 v77, v211
	v_mov_b32_e32 v66, v206
	v_mov_b32_e32 v67, v207
	v_mov_b32_e32 v64, v204
	v_mov_b32_e32 v65, v205
	v_lshlrev_b32_e32 v84, 16, v28
	v_and_b32_e32 v85, 0xffff0000, v28
	v_lshlrev_b32_e32 v28, 16, v72
	v_lshlrev_b32_e32 v30, 16, v73
	v_and_b32_e32 v31, 0xffff0000, v73
	v_lshlrev_b32_e32 v82, 16, v32
	v_and_b32_e32 v83, 0xffff0000, v32
	v_mul_f32_e32 v32, 0xbfb8aa3b, v28
	v_mul_f32_e32 v33, 0xbfb8aa3b, v29
	v_mul_f32_e32 v34, 0xbfb8aa3b, v30
	v_mul_f32_e32 v35, 0xbfb8aa3b, v31
	v_exp_f32_e32 v32, v32
	v_exp_f32_e32 v33, v33
	v_exp_f32_e32 v34, v34
	v_exp_f32_e32 v35, v35
	v_add_f32_e32 v32, 1.0, v32
	v_add_f32_e32 v33, 1.0, v33
	v_add_f32_e32 v34, 1.0, v34
	v_add_f32_e32 v35, 1.0, v35
	v_rcp_f32_e32 v32, v32
	v_rcp_f32_e32 v33, v33
	v_rcp_f32_e32 v34, v34
	v_rcp_f32_e32 v35, v35
	v_lshlrev_b32_e32 v70, 16, v36
	v_pk_mul_f32 v[28:29], v[32:33], v[28:29]
	v_and_b32_e32 v71, 0xffff0000, v36
	v_pk_mul_f32 v[30:31], v[34:35], v[30:31]
	v_lshlrev_b32_e32 v36, 16, v37
	v_and_b32_e32 v37, 0xffff0000, v37
	v_lshlrev_b32_e32 v78, 16, v40
	v_and_b32_e32 v79, 0xffff0000, v40
	v_lshlrev_b32_e32 v40, 16, v41
	v_and_b32_e32 v41, 0xffff0000, v41
	v_lshlrev_b32_e32 v86, 16, v44
	v_and_b32_e32 v87, 0xffff0000, v44
	v_lshlrev_b32_e32 v44, 16, v45
	v_and_b32_e32 v45, 0xffff0000, v45
	v_lshlrev_b32_e32 v80, 16, v48
	v_and_b32_e32 v81, 0xffff0000, v48
	v_lshlrev_b32_e32 v48, 16, v49
	v_and_b32_e32 v49, 0xffff0000, v49
	v_pk_fma_f32 v[32:33], v[64:65], v[60:61], v[74:75]
	v_pk_fma_f32 v[34:35], v[66:67], v[62:63], v[76:77]
	v_pk_mul_f32 v[28:29], v[28:29], v[32:33]
	v_pk_mul_f32 v[30:31], v[30:31], v[34:35]
	v_cvt_pk_bf16_f32 v28, v28, v29
	v_cvt_pk_bf16_f32 v29, v30, v31
	global_store_dwordx2 v[68:69], v[28:29], off offset:64
	v_mov_b32_e32 v32, v216
	v_mov_b32_e32 v33, v217
	v_mov_b32_e32 v34, v218
	v_mov_b32_e32 v35, v219
	v_mov_b32_e32 v30, v214
	v_mov_b32_e32 v31, v215
	v_mov_b32_e32 v28, v212
	v_mov_b32_e32 v29, v213
	v_max_f32_e32 v57, 0xff800000, v92
	v_max3_f32 v57, v57, v112, v116
	v_sub_f32_e32 v62, v110, v57
	v_sub_f32_e32 v63, v112, v57
	v_sub_f32_e32 v57, v116, v57
	v_exp_f32_e32 v64, v62
	v_exp_f32_e32 v63, v63
	v_exp_f32_e32 v62, v57
	v_mov_b32_e32 v112, v117
	v_fma_f32 v57, v111, v64, 0
	v_mul_f32_e32 v64, v111, v64
	v_pk_mul_f32 v[62:63], v[112:113], v[62:63]
	v_lshl_add_u64 v[60:61], s[90:91], 0, v[114:115]
	v_add_f32_e32 v57, v63, v57
	v_add_f32_e32 v57, v62, v57
	v_rcp_f32_e32 v57, v57
	v_lshl_add_u64 v[60:61], v[60:61], 0, s[2:3]
	v_lshl_add_u64 v[60:61], v[60:61], 0, v[108:109]
	v_mul_f32_e32 v64, v64, v57
	v_mul_f32_e32 v66, v63, v57
	v_pk_fma_f32 v[70:71], v[64:65], v[70:71], 0 op_sel_hi:[0,1,0]
	v_pk_fma_f32 v[72:73], v[64:65], v[82:83], 0 op_sel_hi:[0,1,0]
	v_pk_fma_f32 v[36:37], v[64:65], v[36:37], 0 op_sel_hi:[0,1,0]
	v_pk_fma_f32 v[74:75], v[64:65], v[88:89], 0 op_sel_hi:[0,1,0]
	v_pk_fma_f32 v[76:77], v[64:65], v[118:119], 0 op_sel_hi:[0,1,0]
	v_pk_fma_f32 v[82:83], v[64:65], v[142:143], 0 op_sel_hi:[0,1,0]
	v_pk_fma_f32 v[38:39], v[64:65], v[38:39], 0 op_sel_hi:[0,1,0]
	v_pk_fma_f32 v[64:65], v[64:65], v[148:149], 0 op_sel_hi:[0,1,0]
	v_mul_f32_e32 v62, v62, v57
	v_pk_fma_f32 v[36:37], v[66:67], v[40:41], v[36:37] op_sel_hi:[0,1,1]
	v_pk_fma_f32 v[40:41], v[66:67], v[90:91], v[74:75] op_sel_hi:[0,1,1]
	v_pk_fma_f32 v[74:75], v[66:67], v[138:139], v[76:77] op_sel_hi:[0,1,1]
	v_pk_fma_f32 v[38:39], v[66:67], v[42:43], v[38:39] op_sel_hi:[0,1,1]
	v_pk_fma_f32 v[42:43], v[66:67], v[150:151], v[64:65] op_sel_hi:[0,1,1]
	v_pk_fma_f32 v[44:45], v[62:63], v[44:45], v[40:41] op_sel_hi:[0,1,1]
	v_pk_fma_f32 v[40:41], v[62:63], v[140:141], v[74:75] op_sel_hi:[0,1,1]
	v_pk_fma_f32 v[46:47], v[62:63], v[46:47], v[42:43] op_sel_hi:[0,1,1]
	v_pk_fma_f32 v[48:49], v[62:63], v[48:49], v[36:37] op_sel_hi:[0,1,1]
	v_pk_fma_f32 v[50:51], v[62:63], v[50:51], v[38:39] op_sel_hi:[0,1,1]
	v_cvt_pk_bf16_f32 v38, v40, v41
	v_cvt_pk_bf16_f32 v41, v44, v45
	v_cvt_pk_bf16_f32 v43, v46, v47
	v_lshlrev_b32_e32 v44, 16, v58
	v_and_b32_e32 v45, 0xffff0000, v58
	v_lshlrev_b32_e32 v46, 16, v59
	v_and_b32_e32 v47, 0xffff0000, v59
	v_cvt_pk_bf16_f32 v37, v48, v49
	v_cvt_pk_bf16_f32 v39, v50, v51
	v_mul_f32_e32 v48, 0xbfb8aa3b, v44
	v_mul_f32_e32 v49, 0xbfb8aa3b, v45
	v_mul_f32_e32 v50, 0xbfb8aa3b, v46
	v_mul_f32_e32 v51, 0xbfb8aa3b, v47
	v_exp_f32_e32 v48, v48
	v_exp_f32_e32 v49, v49
	v_exp_f32_e32 v50, v50
	v_exp_f32_e32 v51, v51
	v_add_f32_e32 v48, 1.0, v48
	v_add_f32_e32 v49, 1.0, v49
	v_add_f32_e32 v50, 1.0, v50
	v_add_f32_e32 v51, 1.0, v51
	v_rcp_f32_e32 v48, v48
	v_rcp_f32_e32 v49, v49
	v_rcp_f32_e32 v50, v50
	v_rcp_f32_e32 v51, v51
	v_pk_mul_f32 v[52:53], v[52:53], v[56:57] op_sel_hi:[1,0]
	v_pk_mul_f32 v[54:55], v[54:55], v[56:57] op_sel_hi:[1,0]
	v_pk_mul_f32 v[44:45], v[48:49], v[44:45]
	v_pk_mul_f32 v[46:47], v[50:51], v[46:47]
	v_pk_fma_f32 v[70:71], v[66:67], v[78:79], v[70:71] op_sel_hi:[0,1,1]
	v_pk_fma_f32 v[72:73], v[66:67], v[84:85], v[72:73] op_sel_hi:[0,1,1]
	v_pk_fma_f32 v[76:77], v[66:67], v[144:145], v[82:83] op_sel_hi:[0,1,1]
	v_pk_fma_f32 v[64:65], v[62:63], v[80:81], v[70:71] op_sel_hi:[0,1,1]
	v_pk_fma_f32 v[66:67], v[62:63], v[86:87], v[72:73] op_sel_hi:[0,1,1]
	v_pk_fma_f32 v[70:71], v[62:63], v[146:147], v[76:77] op_sel_hi:[0,1,1]
	v_cvt_pk_bf16_f32 v36, v64, v65
	v_cvt_pk_bf16_f32 v40, v66, v67
	v_cvt_pk_bf16_f32 v42, v70, v71
	v_pk_fma_f32 v[28:29], v[28:29], v[52:53], v[32:33]
	v_pk_fma_f32 v[30:31], v[30:31], v[54:55], v[34:35]
	v_pk_mul_f32 v[28:29], v[44:45], v[28:29]
	v_pk_mul_f32 v[30:31], v[46:47], v[30:31]
	v_cvt_pk_bf16_f32 v28, v28, v29
	v_cvt_pk_bf16_f32 v29, v30, v31
	global_store_dwordx2 v[68:69], v[28:29], off offset:96
	global_store_dwordx4 v[60:61], v[36:39], off offset:1024
	global_store_dwordx4 v[60:61], v[40:43], off offset:1040
	s_cbranch_vccz .LBB0_538
